# grid barrier non-leader spin: s_sleep 1 to s_sleep 4 between polls (less poll traffic at the memory side)
# speedup vs baseline: 1.0080x; 1.0008x over previous
.LBB0_709:
	s_and_b32 s12, s17, 0xff
	s_mov_b64 s[10:11], -1
	s_cmp_lg_u32 s12, 0
	s_mov_b64 s[14:15], -1
	s_sleep 4
	s_cbranch_scc1 .LBB0_712
	v_readlane_b32 s12, v254, 18
	v_readlane_b32 s13, v254, 19
	s_nop 4
	global_load_dword v2, v0, s[12:13] sc1
	s_waitcnt vmcnt(0)
	v_cmp_eq_u32_e32 vcc, 0, v2
	s_cbranch_vccnz .LBB0_714
	s_mov_b64 s[14:15], 0
	s_mov_b64 s[12:13], -1
